# small 64x128 tile K loops: eight fragment reads in flight before the first MFMA, counted lgkmcnt
# speedup vs baseline: 1.0095x; 1.0012x over previous
; #define LAS __attribute__((address_space(3)))
; DI void small_kloop(LAS unsigned char* lds, f32x16& acc, const bf16_t* Ap, const bf16_t* Bp, int K, int nkt, int tid, int wm, int wn, int ql, int h) {
;     ...
;     __syncthreads();
;     SM_ISSUE(0, 0); SM_ISSUE(1, 1); SM_ISSUE(2, 2); SM_ISSUE(3, 3);
;     const int ra = 32 * wm + ql, rb = 32 * wn + ql;
;     const unsigned aoff = (unsigned)ra * 128u, boff = 8192u + (unsigned)rb * 128u, sa = (unsigned)(ra & 7), sb = (unsigned)(rb & 7);
;     int slot = 0, islot = 4;
; #pragma nounroll
;     for (int kt = 0; kt < nkt; ++kt) {
;         asm volatile("s_waitcnt vmcnt(9)" ::: "memory");
;         __builtin_amdgcn_s_barrier();
;         asm volatile("" ::: "memory");
;         SM_ISSUE(kt + 4, islot);
;         const LAS unsigned char* st = lds + slot * SM_STAGE;
; #pragma unroll
;         for (int s = 0; s < 4; ++s) {
;             const bf16x8 a = *(const LAS bf16x8*)(st + aoff + (((unsigned)(2 * s + h) ^ sa) << 4));
;             const bf16x8 b = *(const LAS bf16x8*)(st + boff + (((unsigned)(2 * s + h) ^ sb) << 4));
;             acc = __builtin_amdgcn_mfma_f32_32x32x16_bf16(a, b, acc, 0, 0, 0);
;         }
;         islot = slot; slot = slot == SM_NST - 1 ? 0 : slot + 1;
;     }
; DI void small_merge(LAS unsigned char* lds, const bf16_t* YA, const bf16_t* YB, const bf16_t* W4, const bf16_t* GATES, bf16_t* MB) {
;     ...
;         small_kloop(lds, acc, YA + (size_t)(tm * 64) * 512, W4 + (size_t)(tn * 128) * 512, 512, 8, tid, wm, wn, ql, h);
;         small_kloop(lds, acc2, YB + (size_t)(tm * 64) * 512, W4 + (size_t)(1024 + tn * 128) * 512, 512, 8, tid, wm, wn, ql, h);
.LBB0_1601:
	s_mov_b32 s9, s0
	s_min_u32 s0, s7, 3
	s_mul_i32 s1, s14, 0x6000
	s_lshl_b32 s68, s0, 7
	v_add_u32_e32 v44, s1, v49
	v_lshl_add_u64 v[42:43], v[16:17], 0, s[68:69]
	v_readfirstlane_b32 s0, v44
	s_waitcnt vmcnt(9)
	s_barrier
	v_lshl_add_u64 v[42:43], v[42:43], 0, s[60:61]
	s_mov_b32 m0, s0
	v_add_u32_e32 v45, 0x2000, v44
	global_load_lds_dwordx4 v[42:43], off
	v_lshl_add_u64 v[42:43], v[18:19], 0, s[68:69]
	v_readfirstlane_b32 s0, v45
	v_lshl_add_u64 v[42:43], v[42:43], 0, s[60:61]
	s_mov_b32 m0, s0
	v_add_u32_e32 v44, 0x4000, v44
	global_load_lds_dwordx4 v[42:43], off
	v_lshl_add_u64 v[42:43], v[20:21], 0, s[68:69]
	v_readfirstlane_b32 s0, v44
	v_lshl_add_u64 v[42:43], v[42:43], 0, s[60:61]
	s_mov_b32 m0, s0
	s_mul_i32 s0, s9, 0x6000
	global_load_lds_dwordx4 v[42:43], off
	s_add_i32 s0, s0, 0
	s_add_i32 s1, s0, s4
	v_add_u32_e32 v46, s1, v50
	v_add_u32_e32 v42, v46, v51
	ds_read_b128 v[42:45], v42
	s_add_i32 s0, s0, s5
	v_add_u32_e32 v47, s0, v50
	v_add_u32_e32 v58, v47, v51
	ds_read_b128 v[58:61], v58 offset:8192
	s_add_i32 s0, s9, 1
	v_add_u32_e32 v98, v46, v52
	ds_read_b128 v[98:101], v98
	v_add_u32_e32 v102, v47, v52
	ds_read_b128 v[102:105], v102 offset:8192
	s_cmp_lg_u32 s9, 4
	s_cselect_b32 s0, s0, 0
	s_add_i32 s7, s7, 1
	v_add_u32_e32 v106, v46, v53
	ds_read_b128 v[106:109], v106
	v_add_u32_e32 v110, v47, v53
	ds_read_b128 v[110:113], v110 offset:8192
	s_cmp_lg_u32 s7, 8
	s_mov_b32 s14, s9
	v_add_u32_e32 v114, v46, v54
	ds_read_b128 v[114:117], v114
	v_add_u32_e32 v46, v47, v54
	ds_read_b128 v[118:121], v46 offset:8192
	s_waitcnt lgkmcnt(6)
	v_mfma_f32_32x32x16_bf16 v[0:15], v[42:45], v[58:61], v[0:15]
	s_waitcnt lgkmcnt(4)
	v_mfma_f32_32x32x16_bf16 v[0:15], v[98:101], v[102:105], v[0:15]
	s_waitcnt lgkmcnt(2)
	v_mfma_f32_32x32x16_bf16 v[0:15], v[106:109], v[110:113], v[0:15]
	s_waitcnt lgkmcnt(0)
	v_mfma_f32_32x32x16_bf16 v[0:15], v[114:117], v[118:121], v[0:15]
	s_cbranch_scc1 .LBB0_1601
	s_add_u32 s0, s12, 0x100000
	s_addc_u32 s1, s13, 0
	v_lshl_add_u64 v[16:17], v[32:33], 1, s[0:1]
	v_lshl_add_u64 v[44:45], v[16:17], 0, v[34:35]
	v_lshl_add_u64 v[16:17], v[38:39], 1, s[0:1]
	v_readfirstlane_b32 s0, v49
	v_lshl_add_u64 v[42:43], s[10:11], 1, v[40:41]
	s_mov_b32 m0, s0
	v_readfirstlane_b32 s0, v22
	s_waitcnt vmcnt(0)
	s_barrier
	s_waitcnt vmcnt(0)
	s_barrier
	global_load_lds_dwordx4 v[42:43], off
	s_mov_b32 m0, s0
	v_readfirstlane_b32 s0, v23
	v_lshl_add_u64 v[46:47], v[16:17], 0, v[34:35]
	global_load_lds_dwordx4 v[44:45], off
	s_mov_b32 m0, s0
	v_readfirstlane_b32 s0, v24
	global_load_lds_dwordx4 v[46:47], off
	v_lshl_add_u64 v[16:17], v[42:43], 0, s[36:37]
	s_mov_b32 m0, s0
	v_readfirstlane_b32 s0, v25
	global_load_lds_dwordx4 v[16:17], off
	v_lshl_add_u64 v[16:17], v[44:45], 0, s[36:37]
	s_mov_b32 m0, s0
	v_readfirstlane_b32 s0, v26
	global_load_lds_dwordx4 v[16:17], off
	v_lshl_add_u64 v[16:17], v[46:47], 0, s[36:37]
	s_mov_b32 m0, s0
	s_mov_b64 s[10:11], 0x100
	v_readfirstlane_b32 s0, v27
	global_load_lds_dwordx4 v[16:17], off
	v_lshl_add_u64 v[16:17], v[42:43], 0, s[10:11]
	s_mov_b32 m0, s0
	v_readfirstlane_b32 s0, v28
	global_load_lds_dwordx4 v[16:17], off
	v_lshl_add_u64 v[16:17], v[44:45], 0, s[10:11]
	s_mov_b32 m0, s0
	v_readfirstlane_b32 s0, v57
	global_load_lds_dwordx4 v[16:17], off
	v_lshl_add_u64 v[16:17], v[46:47], 0, s[10:11]
	s_mov_b32 m0, s0
	s_mov_b64 s[10:11], 0x180
	v_readfirstlane_b32 s0, v29
	global_load_lds_dwordx4 v[16:17], off
	v_lshl_add_u64 v[16:17], v[42:43], 0, s[10:11]
	s_mov_b32 m0, s0
	v_readfirstlane_b32 s0, v30
	global_load_lds_dwordx4 v[16:17], off
	v_lshl_add_u64 v[16:17], v[44:45], 0, s[10:11]
	s_mov_b32 m0, s0
	v_readfirstlane_b32 s0, v31
	global_load_lds_dwordx4 v[16:17], off
	v_lshl_add_u64 v[16:17], v[46:47], 0, s[10:11]
	s_mov_b32 m0, s0
	s_mov_b32 s10, 4
	global_load_lds_dwordx4 v[16:17], off
	v_mov_b32_e32 v16, 0
	s_mov_b32 s0, 0
	s_mov_b32 s7, 0
	v_mov_b32_e32 v17, v16
	v_mov_b32_e32 v18, v16
	v_mov_b32_e32 v19, v16
	v_mov_b32_e32 v20, v16
	v_mov_b32_e32 v21, v16
	v_mov_b32_e32 v22, v16
	v_mov_b32_e32 v23, v16
	v_mov_b32_e32 v24, v16
	v_mov_b32_e32 v25, v16
	v_mov_b32_e32 v26, v16
	v_mov_b32_e32 v27, v16
	v_mov_b32_e32 v28, v16
	v_mov_b32_e32 v29, v16
	v_mov_b32_e32 v30, v16
	v_mov_b32_e32 v31, v16
; #define LAS __attribute__((address_space(3)))
; DI unsigned pk2(float lo, float hi) { f32x2 v = {lo, hi}; hbf2 r = __builtin_convertvector(v, hbf2); return __builtin_bit_cast(unsigned, r); }
; DI void small_kloop(LAS unsigned char* lds, f32x16& acc, const bf16_t* Ap, const bf16_t* Bp, int K, int nkt, int tid, int wm, int wn, int ql, int h) {
;     ...
; #pragma unroll
;         for (int s = 0; s < 4; ++s) {
;             const bf16x8 a = *(const LAS bf16x8*)(st + aoff + (((unsigned)(2 * s + h) ^ sa) << 4));
;             const bf16x8 b = *(const LAS bf16x8*)(st + boff + (((unsigned)(2 * s + h) ^ sb) << 4));
;             acc = __builtin_amdgcn_mfma_f32_32x32x16_bf16(a, b, acc, 0, 0, 0);
;         }
;         islot = slot; slot = slot == SM_NST - 1 ? 0 : slot + 1;
; DI void small_merge(LAS unsigned char* lds, const bf16_t* YA, const bf16_t* YB, const bf16_t* W4, const bf16_t* GATES, bf16_t* MB) {
;     ...
;         const int col = tn * 128 + 32 * wn + ql;
; #pragma unroll
;         for (int r = 0; r < 16; ++r) {
;             const int rl = 32 * wm + (r & 3) + 8 * (r >> 2) + 4 * h; const size_t row = (size_t)(tm * 64 + rl);
;             const float ga = __uint_as_float((unsigned)GATES[row * 2048 + col] << 16), gb = __uint_as_float((unsigned)GATES[row * 2048 + 1024 + col] << 16);
;             MB[row * DM + col] = (bf16_t)(pk2(ga * acc[r] + gb * acc2[r], 0.f) & 0xffffu);
;         }
.LBB0_1603:
	s_mov_b32 s9, s0
	s_min_u32 s0, s7, 3
	s_mul_i32 s1, s10, 0x6000
	s_lshl_b32 s68, s0, 7
	v_add_u32_e32 v60, s1, v49
	v_lshl_add_u64 v[58:59], v[42:43], 0, s[68:69]
	v_readfirstlane_b32 s0, v60
	s_waitcnt vmcnt(9)
	s_barrier
	v_lshl_add_u64 v[58:59], v[58:59], 0, s[60:61]
	s_mov_b32 m0, s0
	v_add_u32_e32 v61, 0x2000, v60
	global_load_lds_dwordx4 v[58:59], off
	v_lshl_add_u64 v[58:59], v[44:45], 0, s[68:69]
	v_readfirstlane_b32 s0, v61
	v_lshl_add_u64 v[58:59], v[58:59], 0, s[60:61]
	s_mov_b32 m0, s0
	v_add_u32_e32 v60, 0x4000, v60
	global_load_lds_dwordx4 v[58:59], off
	v_lshl_add_u64 v[58:59], v[46:47], 0, s[68:69]
	v_readfirstlane_b32 s0, v60
	v_lshl_add_u64 v[58:59], v[58:59], 0, s[60:61]
	s_mov_b32 m0, s0
	s_mul_i32 s0, s9, 0x6000
	global_load_lds_dwordx4 v[58:59], off
	s_add_i32 s0, s0, 0
	s_add_i32 s1, s0, s4
	v_add_u32_e32 v66, s1, v50
	v_add_u32_e32 v58, v66, v51
	ds_read_b128 v[58:61], v58
	s_add_i32 s0, s0, s5
	v_add_u32_e32 v67, s0, v50
	v_add_u32_e32 v62, v67, v51
	ds_read_b128 v[62:65], v62 offset:8192
	s_add_i32 s0, s9, 1
	v_add_u32_e32 v98, v66, v52
	ds_read_b128 v[98:101], v98
	v_add_u32_e32 v102, v67, v52
	ds_read_b128 v[102:105], v102 offset:8192
	s_cmp_lg_u32 s9, 4
	s_cselect_b32 s0, s0, 0
	s_add_i32 s7, s7, 1
	v_add_u32_e32 v106, v66, v53
	ds_read_b128 v[106:109], v106
	v_add_u32_e32 v110, v67, v53
	ds_read_b128 v[110:113], v110 offset:8192
	s_cmp_lg_u32 s7, 8
	s_mov_b32 s10, s9
	v_add_u32_e32 v114, v66, v54
	ds_read_b128 v[114:117], v114
	v_add_u32_e32 v118, v67, v54
	ds_read_b128 v[118:121], v118 offset:8192
	s_waitcnt lgkmcnt(6)
	v_mfma_f32_32x32x16_bf16 v[16:31], v[58:61], v[62:65], v[16:31]
	s_waitcnt lgkmcnt(4)
	v_mfma_f32_32x32x16_bf16 v[16:31], v[98:101], v[102:105], v[16:31]
	s_waitcnt lgkmcnt(2)
	v_mfma_f32_32x32x16_bf16 v[16:31], v[106:109], v[110:113], v[16:31]
	s_waitcnt lgkmcnt(0)
	v_mfma_f32_32x32x16_bf16 v[16:31], v[114:117], v[118:121], v[16:31]
	s_cbranch_scc1 .LBB0_1603
	v_readlane_b32 s0, v248, 9
	v_readlane_b32 s1, v248, 10
	v_readlane_b32 s12, v248, 11
	v_readlane_b32 s13, v248, 12
	s_lshl_b32 s10, s2, 1
	s_waitcnt vmcnt(0)
	s_barrier
	s_nop 2
	v_add_u32_e32 v96, s8, v56
	v_or_b32_e32 v96, 0, v96
	v_lshlrev_b32_e32 v96, 12, v96
	v_lshl_or_b32 v96, v55, 1, v96
	v_or_b32_e32 v96, s10, v96
	global_load_ushort v42, v96, s[0:1]
	global_load_ushort v43, v96, s[0:1] offset:2048
	v_add_u32_e32 v96, s8, v56
	v_or_b32_e32 v96, 1, v96
	v_lshlrev_b32_e32 v96, 12, v96
	v_lshl_or_b32 v96, v55, 1, v96
	v_or_b32_e32 v96, s10, v96
	global_load_ushort v44, v96, s[0:1]
	global_load_ushort v45, v96, s[0:1] offset:2048
	v_add_u32_e32 v96, s8, v56
	v_or_b32_e32 v96, 2, v96
	v_lshlrev_b32_e32 v96, 12, v96
	v_lshl_or_b32 v96, v55, 1, v96
	v_or_b32_e32 v96, s10, v96
	global_load_ushort v46, v96, s[0:1]
	global_load_ushort v47, v96, s[0:1] offset:2048
	v_add_u32_e32 v96, s8, v56
	v_or_b32_e32 v96, 3, v96
	v_lshlrev_b32_e32 v96, 12, v96
	v_lshl_or_b32 v96, v55, 1, v96
	v_or_b32_e32 v96, s10, v96
	global_load_ushort v58, v96, s[0:1]
	global_load_ushort v59, v96, s[0:1] offset:2048
	v_add_u32_e32 v96, s8, v56
	v_or_b32_e32 v96, 8, v96
	v_lshlrev_b32_e32 v96, 12, v96
	v_lshl_or_b32 v96, v55, 1, v96
	v_or_b32_e32 v96, s10, v96
	global_load_ushort v60, v96, s[0:1]
	global_load_ushort v61, v96, s[0:1] offset:2048
	v_add_u32_e32 v96, s8, v56
	v_or_b32_e32 v96, 9, v96
	v_lshlrev_b32_e32 v96, 12, v96
	v_lshl_or_b32 v96, v55, 1, v96
	v_or_b32_e32 v96, s10, v96
	global_load_ushort v62, v96, s[0:1]
	global_load_ushort v63, v96, s[0:1] offset:2048
	v_add_u32_e32 v96, s8, v56
	v_or_b32_e32 v96, 10, v96
	v_lshlrev_b32_e32 v96, 12, v96
	v_lshl_or_b32 v96, v55, 1, v96
	v_or_b32_e32 v96, s10, v96
	global_load_ushort v64, v96, s[0:1]
	global_load_ushort v65, v96, s[0:1] offset:2048
	v_add_u32_e32 v96, s8, v56
	v_or_b32_e32 v96, 11, v96
	v_lshlrev_b32_e32 v96, 12, v96
	v_lshl_or_b32 v96, v55, 1, v96
	v_or_b32_e32 v96, s10, v96
	global_load_ushort v66, v96, s[0:1]
	global_load_ushort v67, v96, s[0:1] offset:2048
	s_waitcnt vmcnt(0)
	v_lshlrev_b32_e32 v42, 16, v42
	v_lshlrev_b32_e32 v43, 16, v43
	v_mul_f32_e32 v16, v16, v43
	v_fmac_f32_e32 v16, v0, v42
	v_lshlrev_b32_e32 v44, 16, v44
	v_lshlrev_b32_e32 v45, 16, v45
	v_mul_f32_e32 v17, v17, v45
	v_fmac_f32_e32 v17, v1, v44
	v_lshlrev_b32_e32 v46, 16, v46
	v_lshlrev_b32_e32 v47, 16, v47
	v_mul_f32_e32 v18, v18, v47
	v_fmac_f32_e32 v18, v2, v46
	v_lshlrev_b32_e32 v58, 16, v58
	v_lshlrev_b32_e32 v59, 16, v59
	v_mul_f32_e32 v19, v19, v59
	v_fmac_f32_e32 v19, v3, v58
	v_lshlrev_b32_e32 v60, 16, v60
	v_lshlrev_b32_e32 v61, 16, v61
	v_mul_f32_e32 v20, v20, v61
	v_fmac_f32_e32 v20, v4, v60
	v_lshlrev_b32_e32 v62, 16, v62
	v_lshlrev_b32_e32 v63, 16, v63
	v_mul_f32_e32 v21, v21, v63
	v_fmac_f32_e32 v21, v5, v62
	v_lshlrev_b32_e32 v64, 16, v64
	v_lshlrev_b32_e32 v65, 16, v65
	v_mul_f32_e32 v22, v22, v65
	v_fmac_f32_e32 v22, v6, v64
	v_lshlrev_b32_e32 v66, 16, v66
	v_lshlrev_b32_e32 v67, 16, v67
	v_mul_f32_e32 v23, v23, v67
	v_fmac_f32_e32 v23, v7, v66
	v_add_u32_e32 v96, s8, v56
	v_or_b32_e32 v96, 16, v96
	v_lshlrev_b32_e32 v96, 12, v96
	v_lshl_or_b32 v96, v55, 1, v96
	v_or_b32_e32 v96, s10, v96
	global_load_ushort v42, v96, s[0:1]
	global_load_ushort v43, v96, s[0:1] offset:2048
	v_add_u32_e32 v96, s8, v56
	v_or_b32_e32 v96, 17, v96
	v_lshlrev_b32_e32 v96, 12, v96
	v_lshl_or_b32 v96, v55, 1, v96
	v_or_b32_e32 v96, s10, v96
	global_load_ushort v44, v96, s[0:1]
	global_load_ushort v45, v96, s[0:1] offset:2048
	v_add_u32_e32 v96, s8, v56
	v_or_b32_e32 v96, 18, v96
	v_lshlrev_b32_e32 v96, 12, v96
	v_lshl_or_b32 v96, v55, 1, v96
	v_or_b32_e32 v96, s10, v96
	global_load_ushort v46, v96, s[0:1]
; DI unsigned pk2(float lo, float hi) { f32x2 v = {lo, hi}; hbf2 r = __builtin_convertvector(v, hbf2); return __builtin_bit_cast(unsigned, r); }
; DI void small_merge(LAS unsigned char* lds, const bf16_t* YA, const bf16_t* YB, const bf16_t* W4, const bf16_t* GATES, bf16_t* MB) {
;     ...
;         for (int r = 0; r < 16; ++r) {
;             const int rl = 32 * wm + (r & 3) + 8 * (r >> 2) + 4 * h; const size_t row = (size_t)(tm * 64 + rl);
;             const float ga = __uint_as_float((unsigned)GATES[row * 2048 + col] << 16), gb = __uint_as_float((unsigned)GATES[row * 2048 + 1024 + col] << 16);
;             MB[row * DM + col] = (bf16_t)(pk2(ga * acc[r] + gb * acc2[r], 0.f) & 0xffffu);
;         }
	global_load_ushort v47, v96, s[0:1] offset:2048
	v_add_u32_e32 v96, s8, v56
	v_or_b32_e32 v96, 19, v96
	v_lshlrev_b32_e32 v96, 12, v96
	v_lshl_or_b32 v96, v55, 1, v96
	v_or_b32_e32 v96, s10, v96
	global_load_ushort v58, v96, s[0:1]
	global_load_ushort v59, v96, s[0:1] offset:2048
	v_add_u32_e32 v96, s8, v56
	v_or_b32_e32 v96, 24, v96
	v_lshlrev_b32_e32 v96, 12, v96
	v_lshl_or_b32 v96, v55, 1, v96
	v_or_b32_e32 v96, s10, v96
	global_load_ushort v60, v96, s[0:1]
	global_load_ushort v61, v96, s[0:1] offset:2048
	v_add_u32_e32 v96, s8, v56
	v_or_b32_e32 v96, 25, v96
	v_lshlrev_b32_e32 v96, 12, v96
	v_lshl_or_b32 v96, v55, 1, v96
	v_or_b32_e32 v96, s10, v96
	global_load_ushort v62, v96, s[0:1]
	global_load_ushort v63, v96, s[0:1] offset:2048
	v_add_u32_e32 v96, s8, v56
	v_or_b32_e32 v96, 26, v96
	v_lshlrev_b32_e32 v96, 12, v96
	v_lshl_or_b32 v96, v55, 1, v96
	v_or_b32_e32 v96, s10, v96
	global_load_ushort v64, v96, s[0:1]
	global_load_ushort v65, v96, s[0:1] offset:2048
	v_add_u32_e32 v96, s8, v56
	v_or_b32_e32 v96, 27, v96
	v_lshlrev_b32_e32 v96, 12, v96
	v_lshl_or_b32 v96, v55, 1, v96
	v_or_b32_e32 v96, s10, v96
	global_load_ushort v66, v96, s[0:1]
	global_load_ushort v67, v96, s[0:1] offset:2048
	v_cvt_pk_bf16_f32 v16, v16, v16
	v_add_u32_e32 v96, s8, v56
	v_or_b32_e32 v96, 0, v96
	v_lshlrev_b32_e32 v96, 11, v96
	v_lshl_or_b32 v96, v55, 1, v96
	v_or_b32_e32 v96, s10, v96
	global_store_short v96, v16, s[12:13]
	v_cvt_pk_bf16_f32 v17, v17, v17
	v_add_u32_e32 v96, s8, v56
	v_or_b32_e32 v96, 1, v96
	v_lshlrev_b32_e32 v96, 11, v96
	v_lshl_or_b32 v96, v55, 1, v96
	v_or_b32_e32 v96, s10, v96
	global_store_short v96, v17, s[12:13]
	v_cvt_pk_bf16_f32 v18, v18, v18
	v_add_u32_e32 v96, s8, v56
	v_or_b32_e32 v96, 2, v96
	v_lshlrev_b32_e32 v96, 11, v96
	v_lshl_or_b32 v96, v55, 1, v96
	v_or_b32_e32 v96, s10, v96
	global_store_short v96, v18, s[12:13]
	v_cvt_pk_bf16_f32 v19, v19, v19
	v_add_u32_e32 v96, s8, v56
	v_or_b32_e32 v96, 3, v96
	v_lshlrev_b32_e32 v96, 11, v96
	v_lshl_or_b32 v96, v55, 1, v96
	v_or_b32_e32 v96, s10, v96
	global_store_short v96, v19, s[12:13]
	v_cvt_pk_bf16_f32 v20, v20, v20
	v_add_u32_e32 v96, s8, v56
	v_or_b32_e32 v96, 8, v96
	v_lshlrev_b32_e32 v96, 11, v96
	v_lshl_or_b32 v96, v55, 1, v96
	v_or_b32_e32 v96, s10, v96
	global_store_short v96, v20, s[12:13]
	v_cvt_pk_bf16_f32 v21, v21, v21
	v_add_u32_e32 v96, s8, v56
	v_or_b32_e32 v96, 9, v96
	v_lshlrev_b32_e32 v96, 11, v96
	v_lshl_or_b32 v96, v55, 1, v96
	v_or_b32_e32 v96, s10, v96
	global_store_short v96, v21, s[12:13]
	v_cvt_pk_bf16_f32 v22, v22, v22
	v_add_u32_e32 v96, s8, v56
	v_or_b32_e32 v96, 10, v96
	v_lshlrev_b32_e32 v96, 11, v96
	v_lshl_or_b32 v96, v55, 1, v96
	v_or_b32_e32 v96, s10, v96
	global_store_short v96, v22, s[12:13]
	v_cvt_pk_bf16_f32 v23, v23, v23
	v_add_u32_e32 v96, s8, v56
	v_or_b32_e32 v96, 11, v96
	v_lshlrev_b32_e32 v96, 11, v96
	v_lshl_or_b32 v96, v55, 1, v96
	v_or_b32_e32 v96, s10, v96
	global_store_short v96, v23, s[12:13]
	s_waitcnt vmcnt(8)
	v_lshlrev_b32_e32 v42, 16, v42
	v_lshlrev_b32_e32 v43, 16, v43
	v_mul_f32_e32 v24, v24, v43
	v_fmac_f32_e32 v24, v8, v42
	v_lshlrev_b32_e32 v44, 16, v44
	v_lshlrev_b32_e32 v45, 16, v45
	v_mul_f32_e32 v25, v25, v45
	v_fmac_f32_e32 v25, v9, v44
	v_lshlrev_b32_e32 v46, 16, v46
	v_lshlrev_b32_e32 v47, 16, v47
	v_mul_f32_e32 v26, v26, v47
	v_fmac_f32_e32 v26, v10, v46
	v_lshlrev_b32_e32 v58, 16, v58
	v_lshlrev_b32_e32 v59, 16, v59
	v_mul_f32_e32 v27, v27, v59
	v_fmac_f32_e32 v27, v11, v58
	v_lshlrev_b32_e32 v60, 16, v60
	v_lshlrev_b32_e32 v61, 16, v61
	v_mul_f32_e32 v28, v28, v61
	v_fmac_f32_e32 v28, v12, v60
	v_lshlrev_b32_e32 v62, 16, v62
	v_lshlrev_b32_e32 v63, 16, v63
	v_mul_f32_e32 v29, v29, v63
	v_fmac_f32_e32 v29, v13, v62
	v_lshlrev_b32_e32 v64, 16, v64
	v_lshlrev_b32_e32 v65, 16, v65
	v_mul_f32_e32 v30, v30, v65
	v_fmac_f32_e32 v30, v14, v64
	v_lshlrev_b32_e32 v66, 16, v66
	v_lshlrev_b32_e32 v67, 16, v67
	v_mul_f32_e32 v31, v31, v67
	v_fmac_f32_e32 v31, v15, v66
	v_cvt_pk_bf16_f32 v24, v24, v24
	v_add_u32_e32 v96, s8, v56
	v_or_b32_e32 v96, 16, v96
	v_lshlrev_b32_e32 v96, 11, v96
	v_lshl_or_b32 v96, v55, 1, v96
	v_or_b32_e32 v96, s10, v96
	global_store_short v96, v24, s[12:13]
	v_cvt_pk_bf16_f32 v25, v25, v25
	v_add_u32_e32 v96, s8, v56
	v_or_b32_e32 v96, 17, v96
	v_lshlrev_b32_e32 v96, 11, v96
	v_lshl_or_b32 v96, v55, 1, v96
	v_or_b32_e32 v96, s10, v96
	global_store_short v96, v25, s[12:13]
	v_cvt_pk_bf16_f32 v26, v26, v26
	v_add_u32_e32 v96, s8, v56
	v_or_b32_e32 v96, 18, v96
	v_lshlrev_b32_e32 v96, 11, v96
	v_lshl_or_b32 v96, v55, 1, v96
	v_or_b32_e32 v96, s10, v96
	global_store_short v96, v26, s[12:13]
	v_cvt_pk_bf16_f32 v27, v27, v27
	v_add_u32_e32 v96, s8, v56
	v_or_b32_e32 v96, 19, v96
	v_lshlrev_b32_e32 v96, 11, v96
	v_lshl_or_b32 v96, v55, 1, v96
	v_or_b32_e32 v96, s10, v96
	global_store_short v96, v27, s[12:13]
	v_cvt_pk_bf16_f32 v28, v28, v28
	v_add_u32_e32 v96, s8, v56
	v_or_b32_e32 v96, 24, v96
	v_lshlrev_b32_e32 v96, 11, v96
	v_lshl_or_b32 v96, v55, 1, v96
	v_or_b32_e32 v96, s10, v96
	global_store_short v96, v28, s[12:13]
	v_cvt_pk_bf16_f32 v29, v29, v29
	v_add_u32_e32 v96, s8, v56
	v_or_b32_e32 v96, 25, v96
	v_lshlrev_b32_e32 v96, 11, v96
	v_lshl_or_b32 v96, v55, 1, v96
	v_or_b32_e32 v96, s10, v96
	global_store_short v96, v29, s[12:13]
	v_cvt_pk_bf16_f32 v30, v30, v30
	v_add_u32_e32 v96, s8, v56
	v_or_b32_e32 v96, 26, v96
	v_lshlrev_b32_e32 v96, 11, v96
	v_lshl_or_b32 v96, v55, 1, v96
	v_or_b32_e32 v96, s10, v96
	global_store_short v96, v30, s[12:13]
	v_cvt_pk_bf16_f32 v31, v31, v31
	v_add_u32_e32 v96, s8, v56
	v_or_b32_e32 v96, 27, v96
	v_lshlrev_b32_e32 v96, 11, v96
	v_lshl_or_b32 v96, v55, 1, v96
	v_or_b32_e32 v96, s10, v96
	global_store_short v96, v31, s[12:13]
	s_add_i32 s6, s6, s3
	s_cmpk_lt_i32 s6, 0x100
	s_cbranch_scc1 .LBB0_1600

; #define LAS __attribute__((address_space(3)))
; DI unsigned pk2(float lo, float hi) { f32x2 v = {lo, hi}; hbf2 r = __builtin_convertvector(v, hbf2); return __builtin_bit_cast(unsigned, r); }
; DI void small_kloop(LAS unsigned char* lds, f32x16& acc, const bf16_t* Ap, const bf16_t* Bp, int K, int nkt, int tid, int wm, int wn, int ql, int h) {
;     ...
; #pragma unroll
;         for (int s = 0; s < 4; ++s) {
;             const bf16x8 a = *(const LAS bf16x8*)(st + aoff + (((unsigned)(2 * s + h) ^ sa) << 4));
;             const bf16x8 b = *(const LAS bf16x8*)(st + boff + (((unsigned)(2 * s + h) ^ sb) << 4));
;             acc = __builtin_amdgcn_mfma_f32_32x32x16_bf16(a, b, acc, 0, 0, 0);
;         }
;         islot = slot; slot = slot == SM_NST - 1 ? 0 : slot + 1;
; DI void small_resid(LAS unsigned char* lds, const bf16_t* A, const bf16_t* Bt, int K, const float* xin, float* X, bf16_t* XB, float* SS, float scale, bool wxb = true) {
;     ...
; #pragma unroll
;         for (int r = 0; r < 16; ++r) {
;             const int rl = 32 * wm + (r & 3) + 8 * (r >> 2) + 4 * h; const size_t e = (size_t)(tm * 64 + rl) * DM + col;
;             const float o = xin[e] + scale * acc[r];
;             X[e] = o; if (wxb) XB[e] = (bf16_t)(pk2(o, 0.f) & 0xffffu);
;             float q = o * o;
;             q += __shfl_xor(q, 1); q += __shfl_xor(q, 2); q += __shfl_xor(q, 4); q += __shfl_xor(q, 8); q += __shfl_xor(q, 16);
;             if (ql == 0) part[rl * 4 + wn] = q;
.LBB0_1707:
	s_mov_b32 s9, s0
	s_min_u32 s0, s7, 11
	s_mul_i32 s1, s10, 0x6000
	s_lshl_b32 s68, s0, 7
	v_add_u32_e32 v77, s1, v31
	v_lshl_add_u64 v[78:79], v[24:25], 0, s[68:69]
	v_readfirstlane_b32 s0, v77
	s_waitcnt vmcnt(9)
	s_barrier
	v_lshl_add_u64 v[78:79], v[78:79], 0, s[60:61]
	s_mov_b32 m0, s0
	v_add_u32_e32 v80, 0x2000, v77
	global_load_lds_dwordx4 v[78:79], off
	v_lshl_add_u64 v[78:79], v[26:27], 0, s[68:69]
	v_readfirstlane_b32 s0, v80
	v_lshl_add_u64 v[78:79], v[78:79], 0, s[60:61]
	s_mov_b32 m0, s0
	v_add_u32_e32 v77, 0x4000, v77
	global_load_lds_dwordx4 v[78:79], off
	v_lshl_add_u64 v[78:79], v[28:29], 0, s[68:69]
	v_readfirstlane_b32 s0, v77
	v_lshl_add_u64 v[78:79], v[78:79], 0, s[60:61]
	s_mov_b32 m0, s0
	s_mul_i32 s0, s9, 0x6000
	global_load_lds_dwordx4 v[78:79], off
	s_add_i32 s0, s0, 0
	s_add_i32 s1, s0, s4
	v_add_u32_e32 v77, s1, v32
	v_add_u32_e32 v78, v77, v33
	ds_read_b128 v[78:81], v78
	s_add_i32 s0, s0, s5
	v_add_u32_e32 v86, s0, v32
	v_add_u32_e32 v82, v86, v33
	ds_read_b128 v[82:85], v82 offset:8192
	s_add_i32 s0, s9, 1
	v_add_u32_e32 v98, v77, v34
	ds_read_b128 v[98:101], v98
	v_add_u32_e32 v102, v86, v34
	ds_read_b128 v[102:105], v102 offset:8192
	s_cmp_lg_u32 s9, 4
	s_cselect_b32 s0, s0, 0
	s_add_i32 s7, s7, 1
	v_add_u32_e32 v106, v77, v35
	ds_read_b128 v[106:109], v106
	v_add_u32_e32 v110, v86, v35
	ds_read_b128 v[110:113], v110 offset:8192
	v_add_u32_e32 v77, v77, v36
	s_cmp_lg_u32 s7, 16
	s_mov_b32 s10, s9
	ds_read_b128 v[114:117], v77
	v_add_u32_e32 v77, v86, v36
	ds_read_b128 v[118:121], v77 offset:8192
	s_waitcnt lgkmcnt(6)
	v_mfma_f32_32x32x16_bf16 v[0:15], v[78:81], v[82:85], v[0:15]
	s_waitcnt lgkmcnt(4)
	v_mfma_f32_32x32x16_bf16 v[0:15], v[98:101], v[102:105], v[0:15]
	s_waitcnt lgkmcnt(2)
	v_mfma_f32_32x32x16_bf16 v[0:15], v[106:109], v[110:113], v[0:15]
	s_waitcnt lgkmcnt(0)
	v_mfma_f32_32x32x16_bf16 v[0:15], v[114:117], v[118:121], v[0:15]
	s_cbranch_scc1 .LBB0_1707
	v_lshl_or_b32 v24, s2, 7, v58
	v_lshlrev_b32_e32 v24, 2, v24
	s_waitcnt vmcnt(0)
	s_barrier
	v_add_u32_e32 v85, s8, v38
	v_lshl_add_u32 v85, v85, 12, v24
	global_load_dword v77, v85, s[62:63]
	v_add_u32_e32 v86, s8, v39
	v_lshl_add_u32 v86, v86, 12, v24
	global_load_dword v78, v86, s[62:63]
	v_add_u32_e32 v85, s8, v40
	v_lshl_add_u32 v85, v85, 12, v24
	global_load_dword v79, v85, s[62:63]
	v_add_u32_e32 v86, s8, v41
	v_lshl_add_u32 v86, v86, 12, v24
	global_load_dword v80, v86, s[62:63]
	v_add_u32_e32 v85, s8, v42
	v_lshl_add_u32 v85, v85, 12, v24
	global_load_dword v81, v85, s[62:63]
	v_add_u32_e32 v86, s8, v43
	v_lshl_add_u32 v86, v86, 12, v24
	global_load_dword v82, v86, s[62:63]
	v_add_u32_e32 v85, s8, v44
	v_lshl_add_u32 v85, v85, 12, v24
	global_load_dword v83, v85, s[62:63]
	v_add_u32_e32 v86, s8, v45
	v_lshl_add_u32 v86, v86, 12, v24
	global_load_dword v84, v86, s[62:63]
	s_waitcnt vmcnt(0)
	v_add_f32_e32 v0, v0, v77
	v_add_f32_e32 v1, v1, v78
	v_add_f32_e32 v2, v2, v79
	v_add_f32_e32 v3, v3, v80
	v_add_f32_e32 v4, v4, v81
	v_add_f32_e32 v5, v5, v82
	v_add_f32_e32 v6, v6, v83
	v_add_f32_e32 v7, v7, v84
	v_add_u32_e32 v85, s8, v46
	v_lshl_add_u32 v85, v85, 12, v24
	global_load_dword v77, v85, s[62:63]
	v_add_u32_e32 v86, s8, v47
	v_lshl_add_u32 v86, v86, 12, v24
	global_load_dword v78, v86, s[62:63]
	v_add_u32_e32 v85, s8, v48
	v_lshl_add_u32 v85, v85, 12, v24
	global_load_dword v79, v85, s[62:63]
	v_add_u32_e32 v86, s8, v49
	v_lshl_add_u32 v86, v86, 12, v24
	global_load_dword v80, v86, s[62:63]
	v_add_u32_e32 v85, s8, v50
	v_lshl_add_u32 v85, v85, 12, v24
	global_load_dword v81, v85, s[62:63]
	v_add_u32_e32 v86, s8, v51
	v_lshl_add_u32 v86, v86, 12, v24
	global_load_dword v82, v86, s[62:63]
	v_add_u32_e32 v85, s8, v52
	v_lshl_add_u32 v85, v85, 12, v24
	global_load_dword v83, v85, s[62:63]
	v_add_u32_e32 v86, s8, v53
	v_lshl_add_u32 v86, v86, 12, v24
	global_load_dword v84, v86, s[62:63]
	v_add_u32_e32 v85, s8, v38
	v_lshl_add_u32 v85, v85, 12, v24
	global_store_dword v85, v0, s[62:63]
	v_add_u32_e32 v86, s8, v39
	v_lshl_add_u32 v86, v86, 12, v24
	global_store_dword v86, v1, s[62:63]
	v_add_u32_e32 v85, s8, v40
	v_lshl_add_u32 v85, v85, 12, v24
	global_store_dword v85, v2, s[62:63]
	v_add_u32_e32 v86, s8, v41
	v_lshl_add_u32 v86, v86, 12, v24
	global_store_dword v86, v3, s[62:63]
	v_add_u32_e32 v85, s8, v42
	v_lshl_add_u32 v85, v85, 12, v24
	global_store_dword v85, v4, s[62:63]
	v_add_u32_e32 v86, s8, v43
	v_lshl_add_u32 v86, v86, 12, v24
	global_store_dword v86, v5, s[62:63]
	v_add_u32_e32 v85, s8, v44
	v_lshl_add_u32 v85, v85, 12, v24
	global_store_dword v85, v6, s[62:63]
	v_add_u32_e32 v86, s8, v45
	v_lshl_add_u32 v86, v86, 12, v24
	global_store_dword v86, v7, s[62:63]
	v_cvt_pk_bf16_f32 v25, v0, v0
	v_add_u32_e32 v85, s8, v38
	v_lshl_add_u32 v85, v85, 12, v24
	v_lshrrev_b32_e32 v85, 1, v85
	global_store_short v85, v25, s[64:65]
	v_cvt_pk_bf16_f32 v26, v1, v1
	v_add_u32_e32 v86, s8, v39
	v_lshl_add_u32 v86, v86, 12, v24
	v_lshrrev_b32_e32 v86, 1, v86
	global_store_short v86, v26, s[64:65]
	v_cvt_pk_bf16_f32 v27, v2, v2
	v_add_u32_e32 v85, s8, v40
	v_lshl_add_u32 v85, v85, 12, v24
	v_lshrrev_b32_e32 v85, 1, v85
	global_store_short v85, v27, s[64:65]
	v_cvt_pk_bf16_f32 v28, v3, v3
	v_add_u32_e32 v86, s8, v41
	v_lshl_add_u32 v86, v86, 12, v24
	v_lshrrev_b32_e32 v86, 1, v86
	global_store_short v86, v28, s[64:65]
	v_cvt_pk_bf16_f32 v25, v4, v4
	v_add_u32_e32 v85, s8, v42
	v_lshl_add_u32 v85, v85, 12, v24
	v_lshrrev_b32_e32 v85, 1, v85
	global_store_short v85, v25, s[64:65]
	v_cvt_pk_bf16_f32 v26, v5, v5
	v_add_u32_e32 v86, s8, v43
	v_lshl_add_u32 v86, v86, 12, v24
	v_lshrrev_b32_e32 v86, 1, v86
	global_store_short v86, v26, s[64:65]
; DI unsigned pk2(float lo, float hi) { f32x2 v = {lo, hi}; hbf2 r = __builtin_convertvector(v, hbf2); return __builtin_bit_cast(unsigned, r); }
; DI void small_resid(LAS unsigned char* lds, const bf16_t* A, const bf16_t* Bt, int K, const float* xin, float* X, bf16_t* XB, float* SS, float scale, bool wxb = true) {
;     ...
;             X[e] = o; if (wxb) XB[e] = (bf16_t)(pk2(o, 0.f) & 0xffffu);
;             float q = o * o;
;             q += __shfl_xor(q, 1); q += __shfl_xor(q, 2); q += __shfl_xor(q, 4); q += __shfl_xor(q, 8); q += __shfl_xor(q, 16);
;             if (ql == 0) part[rl * 4 + wn] = q;
	v_cvt_pk_bf16_f32 v27, v6, v6
	v_add_u32_e32 v85, s8, v44
	v_lshl_add_u32 v85, v85, 12, v24
	v_lshrrev_b32_e32 v85, 1, v85
	global_store_short v85, v27, s[64:65]
	v_cvt_pk_bf16_f32 v28, v7, v7
	v_add_u32_e32 v86, s8, v45
	v_lshl_add_u32 v86, v86, 12, v24
	v_lshrrev_b32_e32 v86, 1, v86
	global_store_short v86, v28, s[64:65]
	v_mul_f32_e32 v0, v0, v0
	v_mul_f32_e32 v1, v1, v1
	v_mul_f32_e32 v2, v2, v2
	v_mul_f32_e32 v3, v3, v3
	v_mul_f32_e32 v4, v4, v4
	v_mul_f32_e32 v5, v5, v5
	v_mul_f32_e32 v6, v6, v6
	v_mul_f32_e32 v7, v7, v7
	v_add_f32_dpp v0, v0, v0 quad_perm:[1,0,3,2] row_mask:0xf bank_mask:0xf
	v_add_f32_dpp v1, v1, v1 quad_perm:[1,0,3,2] row_mask:0xf bank_mask:0xf
	v_add_f32_dpp v2, v2, v2 quad_perm:[1,0,3,2] row_mask:0xf bank_mask:0xf
	v_add_f32_dpp v3, v3, v3 quad_perm:[1,0,3,2] row_mask:0xf bank_mask:0xf
	v_add_f32_dpp v4, v4, v4 quad_perm:[1,0,3,2] row_mask:0xf bank_mask:0xf
	v_add_f32_dpp v5, v5, v5 quad_perm:[1,0,3,2] row_mask:0xf bank_mask:0xf
	v_add_f32_dpp v6, v6, v6 quad_perm:[1,0,3,2] row_mask:0xf bank_mask:0xf
	v_add_f32_dpp v7, v7, v7 quad_perm:[1,0,3,2] row_mask:0xf bank_mask:0xf
	v_add_f32_dpp v0, v0, v0 quad_perm:[2,3,0,1] row_mask:0xf bank_mask:0xf
	v_add_f32_dpp v1, v1, v1 quad_perm:[2,3,0,1] row_mask:0xf bank_mask:0xf
	v_add_f32_dpp v2, v2, v2 quad_perm:[2,3,0,1] row_mask:0xf bank_mask:0xf
	v_add_f32_dpp v3, v3, v3 quad_perm:[2,3,0,1] row_mask:0xf bank_mask:0xf
	v_add_f32_dpp v4, v4, v4 quad_perm:[2,3,0,1] row_mask:0xf bank_mask:0xf
	v_add_f32_dpp v5, v5, v5 quad_perm:[2,3,0,1] row_mask:0xf bank_mask:0xf
	v_add_f32_dpp v6, v6, v6 quad_perm:[2,3,0,1] row_mask:0xf bank_mask:0xf
	v_add_f32_dpp v7, v7, v7 quad_perm:[2,3,0,1] row_mask:0xf bank_mask:0xf
	v_add_f32_dpp v0, v0, v0 row_half_mirror row_mask:0xf bank_mask:0xf
	v_add_f32_dpp v1, v1, v1 row_half_mirror row_mask:0xf bank_mask:0xf
	v_add_f32_dpp v2, v2, v2 row_half_mirror row_mask:0xf bank_mask:0xf
	v_add_f32_dpp v3, v3, v3 row_half_mirror row_mask:0xf bank_mask:0xf
	v_add_f32_dpp v4, v4, v4 row_half_mirror row_mask:0xf bank_mask:0xf
	v_add_f32_dpp v5, v5, v5 row_half_mirror row_mask:0xf bank_mask:0xf
	v_add_f32_dpp v6, v6, v6 row_half_mirror row_mask:0xf bank_mask:0xf
	v_add_f32_dpp v7, v7, v7 row_half_mirror row_mask:0xf bank_mask:0xf
	v_add_f32_dpp v0, v0, v0 row_mirror row_mask:0xf bank_mask:0xf
	v_add_f32_dpp v1, v1, v1 row_mirror row_mask:0xf bank_mask:0xf
	v_add_f32_dpp v2, v2, v2 row_mirror row_mask:0xf bank_mask:0xf
	v_add_f32_dpp v3, v3, v3 row_mirror row_mask:0xf bank_mask:0xf
	v_add_f32_dpp v4, v4, v4 row_mirror row_mask:0xf bank_mask:0xf
	v_add_f32_dpp v5, v5, v5 row_mirror row_mask:0xf bank_mask:0xf
	v_add_f32_dpp v6, v6, v6 row_mirror row_mask:0xf bank_mask:0xf
	v_add_f32_dpp v7, v7, v7 row_mirror row_mask:0xf bank_mask:0xf
	v_add_f32_dpp v0, v0, v0 row_bcast:15 row_mask:0xa bank_mask:0xf
	v_add_f32_dpp v1, v1, v1 row_bcast:15 row_mask:0xa bank_mask:0xf
	v_add_f32_dpp v2, v2, v2 row_bcast:15 row_mask:0xa bank_mask:0xf
	v_add_f32_dpp v3, v3, v3 row_bcast:15 row_mask:0xa bank_mask:0xf
	v_add_f32_dpp v4, v4, v4 row_bcast:15 row_mask:0xa bank_mask:0xf
	v_add_f32_dpp v5, v5, v5 row_bcast:15 row_mask:0xa bank_mask:0xf
	v_add_f32_dpp v6, v6, v6 row_bcast:15 row_mask:0xa bank_mask:0xf
	v_add_f32_dpp v7, v7, v7 row_bcast:15 row_mask:0xa bank_mask:0xf
	s_mov_b32 s0, 0x10000
	s_mov_b32 s1, 0x10000
	s_mov_b64 s[10:11], exec
	s_mov_b64 exec, s[0:1]
	ds_write_b32 v60, v0
	ds_write_b32 v61, v1
	ds_write_b32 v62, v2
	ds_write_b32 v63, v3
	ds_write_b32 v64, v4
	ds_write_b32 v65, v5
	ds_write_b32 v66, v6
	ds_write_b32 v67, v7
	s_mov_b64 exec, s[10:11]
	s_waitcnt vmcnt(8)
; DI unsigned pk2(float lo, float hi) { f32x2 v = {lo, hi}; hbf2 r = __builtin_convertvector(v, hbf2); return __builtin_bit_cast(unsigned, r); }
; DI void small_resid(LAS unsigned char* lds, const bf16_t* A, const bf16_t* Bt, int K, const float* xin, float* X, bf16_t* XB, float* SS, float scale, bool wxb = true) {
;     ...
; #pragma unroll
;         for (int r = 0; r < 16; ++r) {
;             const int rl = 32 * wm + (r & 3) + 8 * (r >> 2) + 4 * h; const size_t e = (size_t)(tm * 64 + rl) * DM + col;
;             const float o = xin[e] + scale * acc[r];
;             X[e] = o; if (wxb) XB[e] = (bf16_t)(pk2(o, 0.f) & 0xffffu);
;             float q = o * o;
;             q += __shfl_xor(q, 1); q += __shfl_xor(q, 2); q += __shfl_xor(q, 4); q += __shfl_xor(q, 8); q += __shfl_xor(q, 16);
;             if (ql == 0) part[rl * 4 + wn] = q;
;         }
;         __syncthreads();
;         if (tid < 128) { const int rl = tid >> 1, pr = tid & 1; SS[(size_t)(tm * 64 + rl) * 16 + tn * 2 + pr] = part[rl * 4 + 2 * pr] + part[rl * 4 + 2 * pr + 1]; }
	v_add_f32_e32 v8, v8, v77
	v_add_f32_e32 v9, v9, v78
	v_add_f32_e32 v10, v10, v79
	v_add_f32_e32 v11, v11, v80
	v_add_f32_e32 v12, v12, v81
	v_add_f32_e32 v13, v13, v82
	v_add_f32_e32 v14, v14, v83
	v_add_f32_e32 v15, v15, v84
	v_add_u32_e32 v85, s8, v46
	v_lshl_add_u32 v85, v85, 12, v24
	global_store_dword v85, v8, s[62:63]
	v_add_u32_e32 v86, s8, v47
	v_lshl_add_u32 v86, v86, 12, v24
	global_store_dword v86, v9, s[62:63]
	v_add_u32_e32 v85, s8, v48
	v_lshl_add_u32 v85, v85, 12, v24
	global_store_dword v85, v10, s[62:63]
	v_add_u32_e32 v86, s8, v49
	v_lshl_add_u32 v86, v86, 12, v24
	global_store_dword v86, v11, s[62:63]
	v_add_u32_e32 v85, s8, v50
	v_lshl_add_u32 v85, v85, 12, v24
	global_store_dword v85, v12, s[62:63]
	v_add_u32_e32 v86, s8, v51
	v_lshl_add_u32 v86, v86, 12, v24
	global_store_dword v86, v13, s[62:63]
	v_add_u32_e32 v85, s8, v52
	v_lshl_add_u32 v85, v85, 12, v24
	global_store_dword v85, v14, s[62:63]
	v_add_u32_e32 v86, s8, v53
	v_lshl_add_u32 v86, v86, 12, v24
	global_store_dword v86, v15, s[62:63]
	v_cvt_pk_bf16_f32 v25, v8, v8
	v_add_u32_e32 v85, s8, v46
	v_lshl_add_u32 v85, v85, 12, v24
	v_lshrrev_b32_e32 v85, 1, v85
	global_store_short v85, v25, s[64:65]
	v_cvt_pk_bf16_f32 v26, v9, v9
	v_add_u32_e32 v86, s8, v47
	v_lshl_add_u32 v86, v86, 12, v24
	v_lshrrev_b32_e32 v86, 1, v86
	global_store_short v86, v26, s[64:65]
	v_cvt_pk_bf16_f32 v27, v10, v10
	v_add_u32_e32 v85, s8, v48
	v_lshl_add_u32 v85, v85, 12, v24
	v_lshrrev_b32_e32 v85, 1, v85
	global_store_short v85, v27, s[64:65]
	v_cvt_pk_bf16_f32 v28, v11, v11
	v_add_u32_e32 v86, s8, v49
	v_lshl_add_u32 v86, v86, 12, v24
	v_lshrrev_b32_e32 v86, 1, v86
	global_store_short v86, v28, s[64:65]
	v_cvt_pk_bf16_f32 v25, v12, v12
	v_add_u32_e32 v85, s8, v50
	v_lshl_add_u32 v85, v85, 12, v24
	v_lshrrev_b32_e32 v85, 1, v85
	global_store_short v85, v25, s[64:65]
	v_cvt_pk_bf16_f32 v26, v13, v13
	v_add_u32_e32 v86, s8, v51
	v_lshl_add_u32 v86, v86, 12, v24
	v_lshrrev_b32_e32 v86, 1, v86
	global_store_short v86, v26, s[64:65]
	v_cvt_pk_bf16_f32 v27, v14, v14
	v_add_u32_e32 v85, s8, v52
	v_lshl_add_u32 v85, v85, 12, v24
	v_lshrrev_b32_e32 v85, 1, v85
	global_store_short v85, v27, s[64:65]
	v_cvt_pk_bf16_f32 v28, v15, v15
	v_add_u32_e32 v86, s8, v53
	v_lshl_add_u32 v86, v86, 12, v24
	v_lshrrev_b32_e32 v86, 1, v86
	global_store_short v86, v28, s[64:65]
	v_mul_f32_e32 v8, v8, v8
	v_mul_f32_e32 v9, v9, v9
	v_mul_f32_e32 v10, v10, v10
	v_mul_f32_e32 v11, v11, v11
	v_mul_f32_e32 v12, v12, v12
	v_mul_f32_e32 v13, v13, v13
	v_mul_f32_e32 v14, v14, v14
	v_mul_f32_e32 v15, v15, v15
	v_add_f32_dpp v8, v8, v8 quad_perm:[1,0,3,2] row_mask:0xf bank_mask:0xf
	v_add_f32_dpp v9, v9, v9 quad_perm:[1,0,3,2] row_mask:0xf bank_mask:0xf
	v_add_f32_dpp v10, v10, v10 quad_perm:[1,0,3,2] row_mask:0xf bank_mask:0xf
	v_add_f32_dpp v11, v11, v11 quad_perm:[1,0,3,2] row_mask:0xf bank_mask:0xf
	v_add_f32_dpp v12, v12, v12 quad_perm:[1,0,3,2] row_mask:0xf bank_mask:0xf
	v_add_f32_dpp v13, v13, v13 quad_perm:[1,0,3,2] row_mask:0xf bank_mask:0xf
	v_add_f32_dpp v14, v14, v14 quad_perm:[1,0,3,2] row_mask:0xf bank_mask:0xf
	v_add_f32_dpp v15, v15, v15 quad_perm:[1,0,3,2] row_mask:0xf bank_mask:0xf
	v_add_f32_dpp v8, v8, v8 quad_perm:[2,3,0,1] row_mask:0xf bank_mask:0xf
	v_add_f32_dpp v9, v9, v9 quad_perm:[2,3,0,1] row_mask:0xf bank_mask:0xf
	v_add_f32_dpp v10, v10, v10 quad_perm:[2,3,0,1] row_mask:0xf bank_mask:0xf
	v_add_f32_dpp v11, v11, v11 quad_perm:[2,3,0,1] row_mask:0xf bank_mask:0xf
	v_add_f32_dpp v12, v12, v12 quad_perm:[2,3,0,1] row_mask:0xf bank_mask:0xf
	v_add_f32_dpp v13, v13, v13 quad_perm:[2,3,0,1] row_mask:0xf bank_mask:0xf
	v_add_f32_dpp v14, v14, v14 quad_perm:[2,3,0,1] row_mask:0xf bank_mask:0xf
	v_add_f32_dpp v15, v15, v15 quad_perm:[2,3,0,1] row_mask:0xf bank_mask:0xf
	v_add_f32_dpp v8, v8, v8 row_half_mirror row_mask:0xf bank_mask:0xf
	v_add_f32_dpp v9, v9, v9 row_half_mirror row_mask:0xf bank_mask:0xf
	v_add_f32_dpp v10, v10, v10 row_half_mirror row_mask:0xf bank_mask:0xf
	v_add_f32_dpp v11, v11, v11 row_half_mirror row_mask:0xf bank_mask:0xf
	v_add_f32_dpp v12, v12, v12 row_half_mirror row_mask:0xf bank_mask:0xf
	v_add_f32_dpp v13, v13, v13 row_half_mirror row_mask:0xf bank_mask:0xf
	v_add_f32_dpp v14, v14, v14 row_half_mirror row_mask:0xf bank_mask:0xf
	v_add_f32_dpp v15, v15, v15 row_half_mirror row_mask:0xf bank_mask:0xf
	v_add_f32_dpp v8, v8, v8 row_mirror row_mask:0xf bank_mask:0xf
	v_add_f32_dpp v9, v9, v9 row_mirror row_mask:0xf bank_mask:0xf
	v_add_f32_dpp v10, v10, v10 row_mirror row_mask:0xf bank_mask:0xf
	v_add_f32_dpp v11, v11, v11 row_mirror row_mask:0xf bank_mask:0xf
	v_add_f32_dpp v12, v12, v12 row_mirror row_mask:0xf bank_mask:0xf
	v_add_f32_dpp v13, v13, v13 row_mirror row_mask:0xf bank_mask:0xf
	v_add_f32_dpp v14, v14, v14 row_mirror row_mask:0xf bank_mask:0xf
	v_add_f32_dpp v15, v15, v15 row_mirror row_mask:0xf bank_mask:0xf
	v_add_f32_dpp v8, v8, v8 row_bcast:15 row_mask:0xa bank_mask:0xf
	v_add_f32_dpp v9, v9, v9 row_bcast:15 row_mask:0xa bank_mask:0xf
	v_add_f32_dpp v10, v10, v10 row_bcast:15 row_mask:0xa bank_mask:0xf
	v_add_f32_dpp v11, v11, v11 row_bcast:15 row_mask:0xa bank_mask:0xf
	v_add_f32_dpp v12, v12, v12 row_bcast:15 row_mask:0xa bank_mask:0xf
	v_add_f32_dpp v13, v13, v13 row_bcast:15 row_mask:0xa bank_mask:0xf
	v_add_f32_dpp v14, v14, v14 row_bcast:15 row_mask:0xa bank_mask:0xf
	v_add_f32_dpp v15, v15, v15 row_bcast:15 row_mask:0xa bank_mask:0xf
	s_mov_b32 s0, 0x10000
	s_mov_b32 s1, 0x10000
	s_mov_b64 s[10:11], exec
	s_mov_b64 exec, s[0:1]
	ds_write_b32 v68, v8
	ds_write_b32 v69, v9
	ds_write_b32 v70, v10
	ds_write_b32 v71, v11
	ds_write_b32 v72, v12
	ds_write_b32 v73, v13
	ds_write_b32 v74, v14
	ds_write_b32 v75, v15
	s_mov_b64 exec, s[10:11]
	s_waitcnt lgkmcnt(0)
	s_barrier
	s_and_saveexec_b64 s[10:11], s[38:39]
	s_cbranch_execz .LBB0_1705
	v_add_u32_e32 v0, s8, v37
	ds_read_b64 v[2:3], v76
	v_ashrrev_i32_e32 v1, 31, v0
	v_readlane_b32 s0, v248, 17
	v_lshlrev_b64 v[0:1], 6, v[0:1]
	v_readlane_b32 s1, v248, 18
	s_lshl_b32 s68, s2, 3
	s_waitcnt lgkmcnt(0)
	v_add_f32_e32 v2, v2, v3
	v_lshl_add_u64 v[0:1], s[0:1], 0, v[0:1]
	v_lshl_add_u64 v[0:1], v[0:1], 0, s[68:69]
	v_lshl_add_u64 v[0:1], v[0:1], 0, v[96:97]
	global_store_dword v[0:1], v2, off
	s_branch .LBB0_1705

; #define LAS __attribute__((address_space(3)))
; DI unsigned pk2(float lo, float hi) { f32x2 v = {lo, hi}; hbf2 r = __builtin_convertvector(v, hbf2); return __builtin_bit_cast(unsigned, r); }
; DI void small_kloop(LAS unsigned char* lds, f32x16& acc, const bf16_t* Ap, const bf16_t* Bp, int K, int nkt, int tid, int wm, int wn, int ql, int h) {
;     ...
; #pragma unroll
;         for (int s = 0; s < 4; ++s) {
;             const bf16x8 a = *(const LAS bf16x8*)(st + aoff + (((unsigned)(2 * s + h) ^ sa) << 4));
;             const bf16x8 b = *(const LAS bf16x8*)(st + boff + (((unsigned)(2 * s + h) ^ sb) << 4));
;             acc = __builtin_amdgcn_mfma_f32_32x32x16_bf16(a, b, acc, 0, 0, 0);
;         }
;         islot = slot; slot = slot == SM_NST - 1 ? 0 : slot + 1;
; DI void small_resid(LAS unsigned char* lds, const bf16_t* A, const bf16_t* Bt, int K, const float* xin, float* X, bf16_t* XB, float* SS, float scale, bool wxb = true) {
;     ...
; #pragma unroll
;         for (int r = 0; r < 16; ++r) {
;             const int rl = 32 * wm + (r & 3) + 8 * (r >> 2) + 4 * h; const size_t e = (size_t)(tm * 64 + rl) * DM + col;
;             const float o = xin[e] + scale * acc[r];
;             X[e] = o; if (wxb) XB[e] = (bf16_t)(pk2(o, 0.f) & 0xffffu);
.LBB0_2044:
	s_mov_b32 s11, s0
	s_min_u32 s0, s10, 39
	s_mul_i32 s1, s16, 0x6000
	s_lshl_b32 s68, s0, 7
	v_add_u32_e32 v77, s1, v31
	v_lshl_add_u64 v[78:79], v[24:25], 0, s[68:69]
	v_readfirstlane_b32 s0, v77
	s_waitcnt vmcnt(9)
	s_barrier
	v_lshl_add_u64 v[78:79], v[78:79], 0, s[60:61]
	s_mov_b32 m0, s0
	v_add_u32_e32 v80, 0x2000, v77
	global_load_lds_dwordx4 v[78:79], off
	v_lshl_add_u64 v[78:79], v[26:27], 0, s[68:69]
	v_readfirstlane_b32 s0, v80
	v_lshl_add_u64 v[78:79], v[78:79], 0, s[60:61]
	s_mov_b32 m0, s0
	v_add_u32_e32 v77, 0x4000, v77
	global_load_lds_dwordx4 v[78:79], off
	v_lshl_add_u64 v[78:79], v[28:29], 0, s[68:69]
	v_readfirstlane_b32 s0, v77
	v_lshl_add_u64 v[78:79], v[78:79], 0, s[60:61]
	s_mov_b32 m0, s0
	s_mul_i32 s0, s11, 0x6000
	global_load_lds_dwordx4 v[78:79], off
	s_add_i32 s0, s0, 0
	s_add_i32 s1, s0, s2
	v_add_u32_e32 v77, s1, v32
	v_add_u32_e32 v78, v77, v33
	ds_read_b128 v[78:81], v78
	s_add_i32 s0, s0, s12
	v_add_u32_e32 v86, s0, v32
	v_add_u32_e32 v82, v86, v33
	ds_read_b128 v[82:85], v82 offset:8192
	s_add_i32 s0, s11, 1
	v_add_u32_e32 v98, v77, v34
	ds_read_b128 v[98:101], v98
	v_add_u32_e32 v102, v86, v34
	ds_read_b128 v[102:105], v102 offset:8192
	s_cmp_lg_u32 s11, 4
	s_cselect_b32 s0, s0, 0
	s_add_i32 s10, s10, 1
	v_add_u32_e32 v106, v77, v35
	ds_read_b128 v[106:109], v106
	v_add_u32_e32 v110, v86, v35
	ds_read_b128 v[110:113], v110 offset:8192
	v_add_u32_e32 v77, v77, v36
	s_cmp_lg_u32 s10, 44
	s_mov_b32 s16, s11
	ds_read_b128 v[114:117], v77
	v_add_u32_e32 v77, v86, v36
	ds_read_b128 v[118:121], v77 offset:8192
	s_waitcnt lgkmcnt(6)
	v_mfma_f32_32x32x16_bf16 v[0:15], v[78:81], v[82:85], v[0:15]
	s_waitcnt lgkmcnt(4)
	v_mfma_f32_32x32x16_bf16 v[0:15], v[98:101], v[102:105], v[0:15]
	s_waitcnt lgkmcnt(2)
	v_mfma_f32_32x32x16_bf16 v[0:15], v[106:109], v[110:113], v[0:15]
	s_waitcnt lgkmcnt(0)
	v_mfma_f32_32x32x16_bf16 v[0:15], v[114:117], v[118:121], v[0:15]
	s_cbranch_scc1 .LBB0_2044
	v_lshl_or_b32 v24, s14, 7, v58
	v_lshlrev_b32_e32 v24, 2, v24
	s_waitcnt vmcnt(0)
	s_barrier
	v_add_u32_e32 v85, s15, v38
	v_lshl_add_u32 v85, v85, 12, v24
	global_load_dword v77, v85, s[6:7]
	v_add_u32_e32 v86, s15, v39
	v_lshl_add_u32 v86, v86, 12, v24
	global_load_dword v78, v86, s[6:7]
	v_add_u32_e32 v85, s15, v40
	v_lshl_add_u32 v85, v85, 12, v24
	global_load_dword v79, v85, s[6:7]
	v_add_u32_e32 v86, s15, v41
	v_lshl_add_u32 v86, v86, 12, v24
	global_load_dword v80, v86, s[6:7]
	v_add_u32_e32 v85, s15, v42
	v_lshl_add_u32 v85, v85, 12, v24
	global_load_dword v81, v85, s[6:7]
	v_add_u32_e32 v86, s15, v43
	v_lshl_add_u32 v86, v86, 12, v24
	global_load_dword v82, v86, s[6:7]
	v_add_u32_e32 v85, s15, v44
	v_lshl_add_u32 v85, v85, 12, v24
	global_load_dword v83, v85, s[6:7]
	v_add_u32_e32 v86, s15, v45
	v_lshl_add_u32 v86, v86, 12, v24
	global_load_dword v84, v86, s[6:7]
	s_waitcnt vmcnt(0)
	v_fma_f32 v0, v0, 0.5, v77
	v_fma_f32 v1, v1, 0.5, v78
	v_fma_f32 v2, v2, 0.5, v79
	v_fma_f32 v3, v3, 0.5, v80
	v_fma_f32 v4, v4, 0.5, v81
	v_fma_f32 v5, v5, 0.5, v82
	v_fma_f32 v6, v6, 0.5, v83
	v_fma_f32 v7, v7, 0.5, v84
	v_add_u32_e32 v85, s15, v46
	v_lshl_add_u32 v85, v85, 12, v24
	global_load_dword v77, v85, s[6:7]
	v_add_u32_e32 v86, s15, v47
	v_lshl_add_u32 v86, v86, 12, v24
	global_load_dword v78, v86, s[6:7]
	v_add_u32_e32 v85, s15, v48
	v_lshl_add_u32 v85, v85, 12, v24
	global_load_dword v79, v85, s[6:7]
	v_add_u32_e32 v86, s15, v49
	v_lshl_add_u32 v86, v86, 12, v24
	global_load_dword v80, v86, s[6:7]
	v_add_u32_e32 v85, s15, v50
	v_lshl_add_u32 v85, v85, 12, v24
	global_load_dword v81, v85, s[6:7]
	v_add_u32_e32 v86, s15, v51
	v_lshl_add_u32 v86, v86, 12, v24
	global_load_dword v82, v86, s[6:7]
	v_add_u32_e32 v85, s15, v52
	v_lshl_add_u32 v85, v85, 12, v24
	global_load_dword v83, v85, s[6:7]
	v_add_u32_e32 v86, s15, v53
	v_lshl_add_u32 v86, v86, 12, v24
	global_load_dword v84, v86, s[6:7]
	v_add_u32_e32 v85, s15, v38
	v_lshl_add_u32 v85, v85, 12, v24
	global_store_dword v85, v0, s[62:63]
	v_add_u32_e32 v86, s15, v39
	v_lshl_add_u32 v86, v86, 12, v24
	global_store_dword v86, v1, s[62:63]
	v_add_u32_e32 v85, s15, v40
	v_lshl_add_u32 v85, v85, 12, v24
	global_store_dword v85, v2, s[62:63]
	v_add_u32_e32 v86, s15, v41
	v_lshl_add_u32 v86, v86, 12, v24
	global_store_dword v86, v3, s[62:63]
	v_add_u32_e32 v85, s15, v42
	v_lshl_add_u32 v85, v85, 12, v24
	global_store_dword v85, v4, s[62:63]
	v_add_u32_e32 v86, s15, v43
	v_lshl_add_u32 v86, v86, 12, v24
	global_store_dword v86, v5, s[62:63]
	v_add_u32_e32 v85, s15, v44
	v_lshl_add_u32 v85, v85, 12, v24
	global_store_dword v85, v6, s[62:63]
	v_add_u32_e32 v86, s15, v45
	v_lshl_add_u32 v86, v86, 12, v24
	global_store_dword v86, v7, s[62:63]
	s_and_b64 vcc, exec, s[38:39]
	s_cbranch_vccnz .Lsr_ffn_noxb0
	v_cvt_pk_bf16_f32 v25, v0, v0
	v_add_u32_e32 v85, s15, v38
	v_lshl_add_u32 v85, v85, 12, v24
	v_lshrrev_b32_e32 v85, 1, v85
	global_store_short v85, v25, s[64:65]
	v_cvt_pk_bf16_f32 v26, v1, v1
	v_add_u32_e32 v86, s15, v39
	v_lshl_add_u32 v86, v86, 12, v24
	v_lshrrev_b32_e32 v86, 1, v86
	global_store_short v86, v26, s[64:65]
	v_cvt_pk_bf16_f32 v27, v2, v2
	v_add_u32_e32 v85, s15, v40
	v_lshl_add_u32 v85, v85, 12, v24
	v_lshrrev_b32_e32 v85, 1, v85
	global_store_short v85, v27, s[64:65]
	v_cvt_pk_bf16_f32 v28, v3, v3
	v_add_u32_e32 v86, s15, v41
	v_lshl_add_u32 v86, v86, 12, v24
	v_lshrrev_b32_e32 v86, 1, v86
	global_store_short v86, v28, s[64:65]
	v_cvt_pk_bf16_f32 v25, v4, v4
	v_add_u32_e32 v85, s15, v42
	v_lshl_add_u32 v85, v85, 12, v24
	v_lshrrev_b32_e32 v85, 1, v85
	global_store_short v85, v25, s[64:65]
	v_cvt_pk_bf16_f32 v26, v5, v5
	v_add_u32_e32 v86, s15, v43
	v_lshl_add_u32 v86, v86, 12, v24
	v_lshrrev_b32_e32 v86, 1, v86
	global_store_short v86, v26, s[64:65]
	v_cvt_pk_bf16_f32 v27, v6, v6
	v_add_u32_e32 v85, s15, v44
	v_lshl_add_u32 v85, v85, 12, v24
	v_lshrrev_b32_e32 v85, 1, v85
	global_store_short v85, v27, s[64:65]
	v_cvt_pk_bf16_f32 v28, v7, v7
	v_add_u32_e32 v86, s15, v45
	v_lshl_add_u32 v86, v86, 12, v24
	v_lshrrev_b32_e32 v86, 1, v86
	global_store_short v86, v28, s[64:65]
